# GEMM k-loops: removed back-to-back s_setprio 0/1 flips and the duplicate lgkmcnt(0) after each barrier (12 no-op instructions per iteration)
# speedup vs baseline: 1.0057x; 1.0057x over previous
.LBB0_259:
	ds_read_b128 v[152:155], v149
	ds_read_b128 v[156:159], v149 offset:1024
	ds_read_b128 v[160:163], v149 offset:2048
	ds_read_b128 v[164:167], v149 offset:3072
	ds_read_b128 v[168:171], v150
	ds_read_b128 v[172:175], v150 offset:1024
	ds_read_b128 v[176:179], v150 offset:2048
	ds_read_b128 v[184:187], v150 offset:3072
	s_add_u32 s24, s22, 0xfffc0080
	s_addc_u32 s25, s23, -1
	s_cmp_eq_u32 s51, 12
	s_cselect_b32 s27, s15, s25
	s_cselect_b32 s26, s47, s24
	s_cselect_b32 s25, s13, s50
	s_cselect_b32 s24, s48, s49
	v_lshl_add_u64 v[144:145], s[22:23], 0, v[136:137]
	s_add_i32 m0, s21, 0xc000
	ds_read_b128 v[188:191], v151
	ds_read_b128 v[192:195], v151 offset:1024
	ds_read_b128 v[196:199], v151 offset:2048
	ds_read_b128 v[200:203], v151 offset:3072
	ds_read_b128 v[204:207], v151 offset:4096
	ds_read_b128 v[208:211], v151 offset:5120
	ds_read_b128 v[212:215], v151 offset:6144
	ds_read_b128 v[216:219], v151 offset:7168
	global_load_lds_dwordx4 v[144:145], off
	v_lshl_add_u64 v[144:145], s[22:23], 0, v[138:139]
	s_add_i32 m0, s21, 0xe000
	s_nop 0
	global_load_lds_dwordx4 v[144:145], off
	s_waitcnt vmcnt(8)
	s_waitcnt lgkmcnt(0)
	s_barrier
	s_setprio 1
	v_mfma_f32_16x16x32_bf16 v[124:127], v[152:155], v[188:191], v[124:127]
	v_mfma_f32_16x16x32_bf16 v[120:123], v[160:163], v[188:191], v[120:123]
	v_mfma_f32_16x16x32_bf16 v[108:111], v[152:155], v[196:199], v[108:111]
	v_mfma_f32_16x16x32_bf16 v[104:107], v[160:163], v[196:199], v[104:107]
	v_mfma_f32_16x16x32_bf16 v[92:95], v[152:155], v[204:207], v[92:95]
	v_mfma_f32_16x16x32_bf16 v[88:91], v[160:163], v[204:207], v[88:91]
	v_mfma_f32_16x16x32_bf16 v[76:79], v[152:155], v[212:215], v[76:79]
	v_mfma_f32_16x16x32_bf16 v[72:75], v[160:163], v[212:215], v[72:75]
	v_mfma_f32_16x16x32_bf16 v[124:127], v[156:159], v[192:195], v[124:127]
	v_mfma_f32_16x16x32_bf16 v[120:123], v[164:167], v[192:195], v[120:123]
	v_mfma_f32_16x16x32_bf16 v[108:111], v[156:159], v[200:203], v[108:111]
	v_mfma_f32_16x16x32_bf16 v[104:107], v[164:167], v[200:203], v[104:107]
	v_mfma_f32_16x16x32_bf16 v[92:95], v[156:159], v[208:211], v[92:95]
	v_mfma_f32_16x16x32_bf16 v[88:91], v[164:167], v[208:211], v[88:91]
	v_mfma_f32_16x16x32_bf16 v[76:79], v[156:159], v[216:219], v[76:79]
	v_mfma_f32_16x16x32_bf16 v[72:75], v[164:167], v[216:219], v[72:75]
	v_mfma_f32_16x16x32_bf16 v[116:119], v[168:171], v[188:191], v[116:119]
	v_mfma_f32_16x16x32_bf16 v[112:115], v[176:179], v[188:191], v[112:115]
	v_mfma_f32_16x16x32_bf16 v[100:103], v[168:171], v[196:199], v[100:103]
	v_mfma_f32_16x16x32_bf16 v[96:99], v[176:179], v[196:199], v[96:99]
	v_mfma_f32_16x16x32_bf16 v[84:87], v[168:171], v[204:207], v[84:87]
	v_mfma_f32_16x16x32_bf16 v[80:83], v[176:179], v[204:207], v[80:83]
	v_mfma_f32_16x16x32_bf16 v[68:71], v[168:171], v[212:215], v[68:71]
	v_mfma_f32_16x16x32_bf16 v[64:67], v[176:179], v[212:215], v[64:67]
	v_mfma_f32_16x16x32_bf16 v[116:119], v[172:175], v[192:195], v[116:119]
	v_mfma_f32_16x16x32_bf16 v[112:115], v[184:187], v[192:195], v[112:115]
	v_mfma_f32_16x16x32_bf16 v[100:103], v[172:175], v[200:203], v[100:103]
	v_mfma_f32_16x16x32_bf16 v[96:99], v[184:187], v[200:203], v[96:99]
	v_mfma_f32_16x16x32_bf16 v[84:87], v[172:175], v[208:211], v[84:87]
	v_mfma_f32_16x16x32_bf16 v[80:83], v[184:187], v[208:211], v[80:83]
	v_mfma_f32_16x16x32_bf16 v[68:71], v[172:175], v[216:219], v[68:71]
	v_mfma_f32_16x16x32_bf16 v[64:67], v[184:187], v[216:219], v[64:67]
	s_setprio 0
	s_barrier
	s_add_i32 s52, s43, s34
	v_lshl_add_u64 v[144:145], s[24:25], 0, v[130:131]
	s_mov_b32 m0, s52
	ds_read_b128 v[188:191], v151 offset:16384
	ds_read_b128 v[192:195], v151 offset:17408
	ds_read_b128 v[196:199], v151 offset:18432
	ds_read_b128 v[200:203], v151 offset:19456
	ds_read_b128 v[204:207], v151 offset:20480
	ds_read_b128 v[208:211], v151 offset:21504
	ds_read_b128 v[212:215], v151 offset:22528
	ds_read_b128 v[216:219], v151 offset:23552
	global_load_lds_dwordx4 v[144:145], off
	s_add_i32 m0, s52, 0x2000
	s_add_u32 s52, s24, 0x40000
	v_lshl_add_u64 v[180:181], s[24:25], 0, v[134:135]
	s_addc_u32 s53, s25, 0
	s_add_i32 s54, s44, s34
	global_load_lds_dwordx4 v[180:181], off
	v_lshl_add_u64 v[220:221], s[52:53], 0, v[130:131]
	s_mov_b32 m0, s54
	v_lshl_add_u64 v[222:223], s[26:27], 0, v[132:133]
	global_load_lds_dwordx4 v[220:221], off
	v_lshl_add_u64 v[220:221], s[52:53], 0, v[134:135]
	s_add_i32 m0, s54, 0x2000
	s_nop 0
	global_load_lds_dwordx4 v[220:221], off
	v_lshl_add_u64 v[220:221], s[26:27], 0, v[128:129]
	s_mov_b32 m0, s21
	s_nop 0
	global_load_lds_dwordx4 v[220:221], off
	s_mov_b32 m0, s36
	s_nop 0
	global_load_lds_dwordx4 v[222:223], off
	s_waitcnt vmcnt(8)
	s_waitcnt lgkmcnt(0)
	s_barrier
	s_setprio 1
	v_mfma_f32_16x16x32_bf16 v[60:63], v[152:155], v[188:191], v[60:63]
	v_mfma_f32_16x16x32_bf16 v[56:59], v[160:163], v[188:191], v[56:59]
	v_mfma_f32_16x16x32_bf16 v[44:47], v[152:155], v[196:199], v[44:47]
	v_mfma_f32_16x16x32_bf16 v[40:43], v[160:163], v[196:199], v[40:43]
	v_mfma_f32_16x16x32_bf16 v[28:31], v[152:155], v[204:207], v[28:31]
	v_mfma_f32_16x16x32_bf16 v[24:27], v[160:163], v[204:207], v[24:27]
	v_mfma_f32_16x16x32_bf16 v[12:15], v[152:155], v[212:215], v[12:15]
	v_mfma_f32_16x16x32_bf16 v[8:11], v[160:163], v[212:215], v[8:11]
	v_mfma_f32_16x16x32_bf16 v[60:63], v[156:159], v[192:195], v[60:63]
	v_mfma_f32_16x16x32_bf16 v[56:59], v[164:167], v[192:195], v[56:59]
	v_mfma_f32_16x16x32_bf16 v[44:47], v[156:159], v[200:203], v[44:47]
	v_mfma_f32_16x16x32_bf16 v[40:43], v[164:167], v[200:203], v[40:43]
	v_mfma_f32_16x16x32_bf16 v[28:31], v[156:159], v[208:211], v[28:31]
	v_mfma_f32_16x16x32_bf16 v[24:27], v[164:167], v[208:211], v[24:27]
	v_mfma_f32_16x16x32_bf16 v[12:15], v[156:159], v[216:219], v[12:15]
	v_mfma_f32_16x16x32_bf16 v[8:11], v[164:167], v[216:219], v[8:11]
	v_mfma_f32_16x16x32_bf16 v[52:55], v[168:171], v[188:191], v[52:55]
	v_mfma_f32_16x16x32_bf16 v[48:51], v[176:179], v[188:191], v[48:51]
	v_mfma_f32_16x16x32_bf16 v[36:39], v[168:171], v[196:199], v[36:39]
	v_mfma_f32_16x16x32_bf16 v[32:35], v[176:179], v[196:199], v[32:35]
	v_mfma_f32_16x16x32_bf16 v[20:23], v[168:171], v[204:207], v[20:23]
	v_mfma_f32_16x16x32_bf16 v[16:19], v[176:179], v[204:207], v[16:19]
	v_mfma_f32_16x16x32_bf16 v[4:7], v[168:171], v[212:215], v[4:7]
	v_mfma_f32_16x16x32_bf16 v[0:3], v[176:179], v[212:215], v[0:3]
	v_mfma_f32_16x16x32_bf16 v[52:55], v[172:175], v[192:195], v[52:55]
	v_mfma_f32_16x16x32_bf16 v[48:51], v[184:187], v[192:195], v[48:51]
	v_mfma_f32_16x16x32_bf16 v[36:39], v[172:175], v[200:203], v[36:39]
	v_mfma_f32_16x16x32_bf16 v[32:35], v[184:187], v[200:203], v[32:35]
	v_mfma_f32_16x16x32_bf16 v[20:23], v[172:175], v[208:211], v[20:23]
	v_mfma_f32_16x16x32_bf16 v[16:19], v[184:187], v[208:211], v[16:19]
	v_mfma_f32_16x16x32_bf16 v[4:7], v[172:175], v[216:219], v[4:7]
	v_mfma_f32_16x16x32_bf16 v[0:3], v[184:187], v[216:219], v[0:3]
	s_setprio 0
	s_barrier
	s_add_i32 s52, 0, 0x18000
	s_add_i32 s53, 0, 0x1c000
	v_add_u32_e32 v164, s52, v147
	v_add_u32_e32 v183, s53, v147
	ds_read_b128 v[152:155], v164
	ds_read_b128 v[156:159], v164 offset:1024
	ds_read_b128 v[160:163], v164 offset:2048
	ds_read_b128 v[164:167], v164 offset:3072
	ds_read_b128 v[168:171], v183
	ds_read_b128 v[172:175], v183 offset:1024
	ds_read_b128 v[176:179], v183 offset:2048
	ds_read_b128 v[184:187], v183 offset:3072
	s_add_u32 s26, s26, 0x40000
	s_addc_u32 s27, s27, 0
	s_mov_b32 m0, s37
	v_lshl_add_u64 v[224:225], s[26:27], 0, v[128:129]
	ds_read_b128 v[188:191], v151 offset:32768
	ds_read_b128 v[192:195], v151 offset:33792
	ds_read_b128 v[196:199], v151 offset:34816
	ds_read_b128 v[200:203], v151 offset:35840
	ds_read_b128 v[204:207], v151 offset:36864
	ds_read_b128 v[208:211], v151 offset:37888
	ds_read_b128 v[212:215], v151 offset:38912
	ds_read_b128 v[216:219], v151 offset:39936
	global_load_lds_dwordx4 v[224:225], off
	v_lshl_add_u64 v[224:225], s[26:27], 0, v[132:133]
	s_mov_b32 m0, s38
	s_nop 0
	global_load_lds_dwordx4 v[224:225], off
	s_waitcnt vmcnt(8)
	s_waitcnt lgkmcnt(0)
	s_barrier
	s_setprio 1
	v_mfma_f32_16x16x32_bf16 v[124:127], v[152:155], v[188:191], v[124:127]
	v_mfma_f32_16x16x32_bf16 v[120:123], v[160:163], v[188:191], v[120:123]
	v_mfma_f32_16x16x32_bf16 v[108:111], v[152:155], v[196:199], v[108:111]
	v_mfma_f32_16x16x32_bf16 v[104:107], v[160:163], v[196:199], v[104:107]
	v_mfma_f32_16x16x32_bf16 v[92:95], v[152:155], v[204:207], v[92:95]
	v_mfma_f32_16x16x32_bf16 v[88:91], v[160:163], v[204:207], v[88:91]
	v_mfma_f32_16x16x32_bf16 v[76:79], v[152:155], v[212:215], v[76:79]
	v_mfma_f32_16x16x32_bf16 v[72:75], v[160:163], v[212:215], v[72:75]
	v_mfma_f32_16x16x32_bf16 v[124:127], v[156:159], v[192:195], v[124:127]
	v_mfma_f32_16x16x32_bf16 v[120:123], v[164:167], v[192:195], v[120:123]
	v_mfma_f32_16x16x32_bf16 v[108:111], v[156:159], v[200:203], v[108:111]
	v_mfma_f32_16x16x32_bf16 v[104:107], v[164:167], v[200:203], v[104:107]
	v_mfma_f32_16x16x32_bf16 v[92:95], v[156:159], v[208:211], v[92:95]
	v_mfma_f32_16x16x32_bf16 v[88:91], v[164:167], v[208:211], v[88:91]
	v_mfma_f32_16x16x32_bf16 v[76:79], v[156:159], v[216:219], v[76:79]
	v_mfma_f32_16x16x32_bf16 v[72:75], v[164:167], v[216:219], v[72:75]
	v_mfma_f32_16x16x32_bf16 v[116:119], v[168:171], v[188:191], v[116:119]
	v_mfma_f32_16x16x32_bf16 v[112:115], v[176:179], v[188:191], v[112:115]
	v_mfma_f32_16x16x32_bf16 v[100:103], v[168:171], v[196:199], v[100:103]
	v_mfma_f32_16x16x32_bf16 v[96:99], v[176:179], v[196:199], v[96:99]
	v_mfma_f32_16x16x32_bf16 v[84:87], v[168:171], v[204:207], v[84:87]
	v_mfma_f32_16x16x32_bf16 v[80:83], v[176:179], v[204:207], v[80:83]
	v_mfma_f32_16x16x32_bf16 v[68:71], v[168:171], v[212:215], v[68:71]
	v_mfma_f32_16x16x32_bf16 v[64:67], v[176:179], v[212:215], v[64:67]
	v_mfma_f32_16x16x32_bf16 v[116:119], v[172:175], v[192:195], v[116:119]
	v_mfma_f32_16x16x32_bf16 v[112:115], v[184:187], v[192:195], v[112:115]
	v_mfma_f32_16x16x32_bf16 v[100:103], v[172:175], v[200:203], v[100:103]
	v_mfma_f32_16x16x32_bf16 v[96:99], v[184:187], v[200:203], v[96:99]
	v_mfma_f32_16x16x32_bf16 v[84:87], v[172:175], v[208:211], v[84:87]
	v_mfma_f32_16x16x32_bf16 v[80:83], v[184:187], v[208:211], v[80:83]
	v_mfma_f32_16x16x32_bf16 v[68:71], v[172:175], v[216:219], v[68:71]
	v_mfma_f32_16x16x32_bf16 v[64:67], v[184:187], v[216:219], v[64:67]
	s_setprio 0
	s_barrier
	s_add_i32 s26, s52, s34
	v_lshl_add_u64 v[144:145], v[144:145], 0, s[8:9]
	s_mov_b32 m0, s26
	ds_read_b128 v[188:191], v151 offset:49152
	ds_read_b128 v[192:195], v151 offset:50176
	ds_read_b128 v[196:199], v151 offset:51200
	ds_read_b128 v[200:203], v151 offset:52224
	ds_read_b128 v[204:207], v151 offset:53248
	ds_read_b128 v[208:211], v151 offset:54272
	ds_read_b128 v[212:215], v151 offset:55296
	ds_read_b128 v[216:219], v151 offset:56320
	global_load_lds_dwordx4 v[144:145], off
	s_add_i32 m0, s26, 0x2000
	s_add_u32 s24, s24, 0x40080
	v_lshl_add_u64 v[144:145], v[180:181], 0, s[8:9]
	s_addc_u32 s25, s25, 0
	s_add_i32 s26, s53, s34
	global_load_lds_dwordx4 v[144:145], off
	v_lshl_add_u64 v[144:145], s[24:25], 0, v[130:131]
	s_mov_b32 m0, s26
	s_nop 0
	global_load_lds_dwordx4 v[144:145], off
	v_lshl_add_u64 v[144:145], s[24:25], 0, v[134:135]
	s_add_i32 m0, s26, 0x2000
	s_nop 0
	global_load_lds_dwordx4 v[144:145], off
	v_lshl_add_u64 v[144:145], v[220:221], 0, s[8:9]
	s_mov_b32 m0, s41
	s_nop 0
	global_load_lds_dwordx4 v[144:145], off
	v_lshl_add_u64 v[144:145], v[222:223], 0, s[8:9]
	s_mov_b32 m0, s42
	s_nop 0
	global_load_lds_dwordx4 v[144:145], off
	s_waitcnt vmcnt(8)
	s_waitcnt lgkmcnt(0)
	s_barrier
	s_setprio 1
	v_mfma_f32_16x16x32_bf16 v[60:63], v[152:155], v[188:191], v[60:63]
	v_mfma_f32_16x16x32_bf16 v[56:59], v[160:163], v[188:191], v[56:59]
	v_mfma_f32_16x16x32_bf16 v[44:47], v[152:155], v[196:199], v[44:47]
	v_mfma_f32_16x16x32_bf16 v[40:43], v[160:163], v[196:199], v[40:43]
	v_mfma_f32_16x16x32_bf16 v[28:31], v[152:155], v[204:207], v[28:31]
	v_mfma_f32_16x16x32_bf16 v[24:27], v[160:163], v[204:207], v[24:27]
	v_mfma_f32_16x16x32_bf16 v[12:15], v[152:155], v[212:215], v[12:15]
	v_mfma_f32_16x16x32_bf16 v[8:11], v[160:163], v[212:215], v[8:11]
	v_mfma_f32_16x16x32_bf16 v[60:63], v[156:159], v[192:195], v[60:63]
	v_mfma_f32_16x16x32_bf16 v[56:59], v[164:167], v[192:195], v[56:59]
	v_mfma_f32_16x16x32_bf16 v[44:47], v[156:159], v[200:203], v[44:47]
	v_mfma_f32_16x16x32_bf16 v[40:43], v[164:167], v[200:203], v[40:43]
	v_mfma_f32_16x16x32_bf16 v[28:31], v[156:159], v[208:211], v[28:31]
	v_mfma_f32_16x16x32_bf16 v[24:27], v[164:167], v[208:211], v[24:27]
	v_mfma_f32_16x16x32_bf16 v[12:15], v[156:159], v[216:219], v[12:15]
	v_mfma_f32_16x16x32_bf16 v[8:11], v[164:167], v[216:219], v[8:11]
	v_mfma_f32_16x16x32_bf16 v[52:55], v[168:171], v[188:191], v[52:55]
	v_mfma_f32_16x16x32_bf16 v[48:51], v[176:179], v[188:191], v[48:51]
	v_mfma_f32_16x16x32_bf16 v[36:39], v[168:171], v[196:199], v[36:39]
	v_mfma_f32_16x16x32_bf16 v[32:35], v[176:179], v[196:199], v[32:35]
	v_mfma_f32_16x16x32_bf16 v[20:23], v[168:171], v[204:207], v[20:23]
	v_mfma_f32_16x16x32_bf16 v[16:19], v[176:179], v[204:207], v[16:19]
	v_mfma_f32_16x16x32_bf16 v[4:7], v[168:171], v[212:215], v[4:7]
	v_mfma_f32_16x16x32_bf16 v[0:3], v[176:179], v[212:215], v[0:3]
	v_mfma_f32_16x16x32_bf16 v[52:55], v[172:175], v[192:195], v[52:55]
	v_mfma_f32_16x16x32_bf16 v[48:51], v[184:187], v[192:195], v[48:51]
	v_mfma_f32_16x16x32_bf16 v[36:39], v[172:175], v[200:203], v[36:39]
	v_mfma_f32_16x16x32_bf16 v[32:35], v[184:187], v[200:203], v[32:35]
	v_mfma_f32_16x16x32_bf16 v[20:23], v[172:175], v[208:211], v[20:23]
	v_mfma_f32_16x16x32_bf16 v[16:19], v[184:187], v[208:211], v[16:19]
	v_mfma_f32_16x16x32_bf16 v[4:7], v[172:175], v[216:219], v[4:7]
	v_mfma_f32_16x16x32_bf16 v[0:3], v[184:187], v[216:219], v[0:3]
	s_setprio 0
	s_barrier
	s_add_i32 s51, s51, 2
	s_add_u32 s22, s22, 0x100
	s_addc_u32 s23, s23, 0
	s_add_u32 s49, s49, 0x100
	s_addc_u32 s50, s50, 0
	s_cmp_gt_u32 s51, 13
	s_cbranch_scc0 .LBB0_259
	s_and_b64 vcc, exec, s[10:11]
	s_cbranch_vccz .LBB0_262
	s_barrier

.LBB0_338:
	ds_read_b128 v[150:153], v147
	ds_read_b128 v[154:157], v147 offset:1024
	ds_read_b128 v[158:161], v147 offset:2048
	ds_read_b128 v[162:165], v147 offset:3072
	ds_read_b128 v[166:169], v148
	ds_read_b128 v[170:173], v148 offset:1024
	ds_read_b128 v[174:177], v148 offset:2048
	ds_read_b128 v[178:181], v148 offset:3072
	s_add_u32 s26, s24, 0xfff50080
	s_addc_u32 s27, s25, -1
	s_cmp_eq_u32 s57, 40
	s_cselect_b32 s29, s5, s27
	s_cselect_b32 s28, s4, s26
	s_cselect_b32 s27, s23, s56
	s_cselect_b32 s26, s22, s55
	v_lshl_add_u64 v[216:217], s[24:25], 0, v[136:137]
	s_add_i32 m0, s37, 0xc000
	ds_read_b128 v[184:187], v149
	ds_read_b128 v[188:191], v149 offset:1024
	ds_read_b128 v[192:195], v149 offset:2048
	ds_read_b128 v[196:199], v149 offset:3072
	ds_read_b128 v[200:203], v149 offset:4096
	ds_read_b128 v[204:207], v149 offset:5120
	ds_read_b128 v[208:211], v149 offset:6144
	ds_read_b128 v[212:215], v149 offset:7168
	global_load_lds_dwordx4 v[216:217], off
	v_lshl_add_u64 v[216:217], s[24:25], 0, v[138:139]
	s_add_i32 m0, s37, 0xe000
	s_nop 0
	global_load_lds_dwordx4 v[216:217], off
	s_waitcnt vmcnt(8)
	s_waitcnt lgkmcnt(0)
	s_barrier
	s_setprio 1
	v_mfma_f32_16x16x32_bf16 v[124:127], v[150:153], v[184:187], v[124:127]
	v_mfma_f32_16x16x32_bf16 v[120:123], v[158:161], v[184:187], v[120:123]
	v_mfma_f32_16x16x32_bf16 v[116:119], v[150:153], v[192:195], v[116:119]
	v_mfma_f32_16x16x32_bf16 v[112:115], v[158:161], v[192:195], v[112:115]
	v_mfma_f32_16x16x32_bf16 v[100:103], v[150:153], v[200:203], v[100:103]
	v_mfma_f32_16x16x32_bf16 v[96:99], v[158:161], v[200:203], v[96:99]
	v_mfma_f32_16x16x32_bf16 v[84:87], v[150:153], v[208:211], v[84:87]
	v_mfma_f32_16x16x32_bf16 v[80:83], v[158:161], v[208:211], v[80:83]
	v_mfma_f32_16x16x32_bf16 v[124:127], v[154:157], v[188:191], v[124:127]
	v_mfma_f32_16x16x32_bf16 v[120:123], v[162:165], v[188:191], v[120:123]
	v_mfma_f32_16x16x32_bf16 v[116:119], v[154:157], v[196:199], v[116:119]
	v_mfma_f32_16x16x32_bf16 v[112:115], v[162:165], v[196:199], v[112:115]
	v_mfma_f32_16x16x32_bf16 v[100:103], v[154:157], v[204:207], v[100:103]
	v_mfma_f32_16x16x32_bf16 v[96:99], v[162:165], v[204:207], v[96:99]
	v_mfma_f32_16x16x32_bf16 v[84:87], v[154:157], v[212:215], v[84:87]
	v_mfma_f32_16x16x32_bf16 v[80:83], v[162:165], v[212:215], v[80:83]
	v_mfma_f32_16x16x32_bf16 v[108:111], v[166:169], v[184:187], v[108:111]
	v_mfma_f32_16x16x32_bf16 v[104:107], v[174:177], v[184:187], v[104:107]
	v_mfma_f32_16x16x32_bf16 v[92:95], v[166:169], v[192:195], v[92:95]
	v_mfma_f32_16x16x32_bf16 v[88:91], v[174:177], v[192:195], v[88:91]
	v_mfma_f32_16x16x32_bf16 v[76:79], v[166:169], v[200:203], v[76:79]
	v_mfma_f32_16x16x32_bf16 v[72:75], v[174:177], v[200:203], v[72:75]
	v_mfma_f32_16x16x32_bf16 v[68:71], v[166:169], v[208:211], v[68:71]
	v_mfma_f32_16x16x32_bf16 v[64:67], v[174:177], v[208:211], v[64:67]
	v_mfma_f32_16x16x32_bf16 v[108:111], v[170:173], v[188:191], v[108:111]
	v_mfma_f32_16x16x32_bf16 v[104:107], v[178:181], v[188:191], v[104:107]
	v_mfma_f32_16x16x32_bf16 v[92:95], v[170:173], v[196:199], v[92:95]
	v_mfma_f32_16x16x32_bf16 v[88:91], v[178:181], v[196:199], v[88:91]
	v_mfma_f32_16x16x32_bf16 v[76:79], v[170:173], v[204:207], v[76:79]
	v_mfma_f32_16x16x32_bf16 v[72:75], v[178:181], v[204:207], v[72:75]
	v_mfma_f32_16x16x32_bf16 v[68:71], v[170:173], v[212:215], v[68:71]
	v_mfma_f32_16x16x32_bf16 v[64:67], v[178:181], v[212:215], v[64:67]
	s_setprio 0
	s_barrier
	s_add_i32 s58, s45, s36
	v_lshl_add_u64 v[216:217], s[26:27], 0, v[130:131]
	s_mov_b32 m0, s58
	ds_read_b128 v[184:187], v149 offset:16384
	ds_read_b128 v[188:191], v149 offset:17408
	ds_read_b128 v[192:195], v149 offset:18432
	ds_read_b128 v[196:199], v149 offset:19456
	ds_read_b128 v[200:203], v149 offset:20480
	ds_read_b128 v[204:207], v149 offset:21504
	ds_read_b128 v[208:211], v149 offset:22528
	ds_read_b128 v[212:215], v149 offset:23552
	global_load_lds_dwordx4 v[216:217], off
	s_add_i32 m0, s58, 0x2000
	s_add_u32 s58, s26, 0xb0000
	v_lshl_add_u64 v[218:219], s[26:27], 0, v[134:135]
	s_addc_u32 s59, s27, 0
	s_add_i32 s60, s46, s36
	global_load_lds_dwordx4 v[218:219], off
	v_lshl_add_u64 v[220:221], s[58:59], 0, v[130:131]
	s_mov_b32 m0, s60
	v_lshl_add_u64 v[222:223], s[28:29], 0, v[132:133]
	global_load_lds_dwordx4 v[220:221], off
	v_lshl_add_u64 v[220:221], s[58:59], 0, v[134:135]
	s_add_i32 m0, s60, 0x2000
	s_nop 0
	global_load_lds_dwordx4 v[220:221], off
	v_lshl_add_u64 v[220:221], s[28:29], 0, v[128:129]
	s_mov_b32 m0, s37
	s_nop 0
	global_load_lds_dwordx4 v[220:221], off
	s_mov_b32 m0, s38
	s_nop 0
	global_load_lds_dwordx4 v[222:223], off
	s_waitcnt vmcnt(8)
	s_waitcnt lgkmcnt(0)
	s_barrier
	s_setprio 1
	v_mfma_f32_16x16x32_bf16 v[60:63], v[150:153], v[184:187], v[60:63]
	v_mfma_f32_16x16x32_bf16 v[56:59], v[158:161], v[184:187], v[56:59]
	v_mfma_f32_16x16x32_bf16 v[52:55], v[150:153], v[192:195], v[52:55]
	v_mfma_f32_16x16x32_bf16 v[48:51], v[158:161], v[192:195], v[48:51]
	v_mfma_f32_16x16x32_bf16 v[36:39], v[150:153], v[200:203], v[36:39]
	v_mfma_f32_16x16x32_bf16 v[32:35], v[158:161], v[200:203], v[32:35]
	v_mfma_f32_16x16x32_bf16 v[20:23], v[150:153], v[208:211], v[20:23]
	v_mfma_f32_16x16x32_bf16 v[16:19], v[158:161], v[208:211], v[16:19]
	v_mfma_f32_16x16x32_bf16 v[60:63], v[154:157], v[188:191], v[60:63]
	v_mfma_f32_16x16x32_bf16 v[56:59], v[162:165], v[188:191], v[56:59]
	v_mfma_f32_16x16x32_bf16 v[52:55], v[154:157], v[196:199], v[52:55]
	v_mfma_f32_16x16x32_bf16 v[48:51], v[162:165], v[196:199], v[48:51]
	v_mfma_f32_16x16x32_bf16 v[36:39], v[154:157], v[204:207], v[36:39]
	v_mfma_f32_16x16x32_bf16 v[32:35], v[162:165], v[204:207], v[32:35]
	v_mfma_f32_16x16x32_bf16 v[20:23], v[154:157], v[212:215], v[20:23]
	v_mfma_f32_16x16x32_bf16 v[16:19], v[162:165], v[212:215], v[16:19]
	v_mfma_f32_16x16x32_bf16 v[44:47], v[166:169], v[184:187], v[44:47]
	v_mfma_f32_16x16x32_bf16 v[40:43], v[174:177], v[184:187], v[40:43]
	v_mfma_f32_16x16x32_bf16 v[28:31], v[166:169], v[192:195], v[28:31]
	v_mfma_f32_16x16x32_bf16 v[24:27], v[174:177], v[192:195], v[24:27]
	v_mfma_f32_16x16x32_bf16 v[12:15], v[166:169], v[200:203], v[12:15]
	v_mfma_f32_16x16x32_bf16 v[8:11], v[174:177], v[200:203], v[8:11]
	v_mfma_f32_16x16x32_bf16 v[4:7], v[166:169], v[208:211], v[4:7]
	v_mfma_f32_16x16x32_bf16 v[0:3], v[174:177], v[208:211], v[0:3]
	v_mfma_f32_16x16x32_bf16 v[44:47], v[170:173], v[188:191], v[44:47]
	v_mfma_f32_16x16x32_bf16 v[40:43], v[178:181], v[188:191], v[40:43]
	v_mfma_f32_16x16x32_bf16 v[28:31], v[170:173], v[196:199], v[28:31]
	v_mfma_f32_16x16x32_bf16 v[24:27], v[178:181], v[196:199], v[24:27]
	v_mfma_f32_16x16x32_bf16 v[12:15], v[170:173], v[204:207], v[12:15]
	v_mfma_f32_16x16x32_bf16 v[8:11], v[178:181], v[204:207], v[8:11]
	v_mfma_f32_16x16x32_bf16 v[4:7], v[170:173], v[212:215], v[4:7]
	v_mfma_f32_16x16x32_bf16 v[0:3], v[178:181], v[212:215], v[0:3]
	s_setprio 0
	s_barrier
	s_add_i32 s58, 0, 0x18000
	s_add_i32 s59, 0, 0x1c000
	v_add_u32_e32 v162, s58, v145
	v_add_u32_e32 v178, s59, v145
	ds_read_b128 v[150:153], v162
	ds_read_b128 v[154:157], v162 offset:1024
	ds_read_b128 v[158:161], v162 offset:2048
	ds_read_b128 v[162:165], v162 offset:3072
	ds_read_b128 v[166:169], v178
	ds_read_b128 v[170:173], v178 offset:1024
	ds_read_b128 v[174:177], v178 offset:2048
	ds_read_b128 v[178:181], v178 offset:3072
	s_add_u32 s28, s28, 0xb0000
	s_addc_u32 s29, s29, 0
	s_mov_b32 m0, s39
	v_lshl_add_u64 v[224:225], s[28:29], 0, v[128:129]
	ds_read_b128 v[184:187], v149 offset:32768
	ds_read_b128 v[188:191], v149 offset:33792
	ds_read_b128 v[192:195], v149 offset:34816
	ds_read_b128 v[196:199], v149 offset:35840
	ds_read_b128 v[200:203], v149 offset:36864
	ds_read_b128 v[204:207], v149 offset:37888
	ds_read_b128 v[208:211], v149 offset:38912
	ds_read_b128 v[212:215], v149 offset:39936
	global_load_lds_dwordx4 v[224:225], off
	v_lshl_add_u64 v[224:225], s[28:29], 0, v[132:133]
	s_mov_b32 m0, s40
	s_nop 0
	global_load_lds_dwordx4 v[224:225], off
	s_waitcnt vmcnt(8)
	s_waitcnt lgkmcnt(0)
	s_barrier
	s_setprio 1
	v_mfma_f32_16x16x32_bf16 v[124:127], v[150:153], v[184:187], v[124:127]
	v_mfma_f32_16x16x32_bf16 v[120:123], v[158:161], v[184:187], v[120:123]
	v_mfma_f32_16x16x32_bf16 v[116:119], v[150:153], v[192:195], v[116:119]
	v_mfma_f32_16x16x32_bf16 v[112:115], v[158:161], v[192:195], v[112:115]
	v_mfma_f32_16x16x32_bf16 v[100:103], v[150:153], v[200:203], v[100:103]
	v_mfma_f32_16x16x32_bf16 v[96:99], v[158:161], v[200:203], v[96:99]
	v_mfma_f32_16x16x32_bf16 v[84:87], v[150:153], v[208:211], v[84:87]
	v_mfma_f32_16x16x32_bf16 v[80:83], v[158:161], v[208:211], v[80:83]
	v_mfma_f32_16x16x32_bf16 v[124:127], v[154:157], v[188:191], v[124:127]
	v_mfma_f32_16x16x32_bf16 v[120:123], v[162:165], v[188:191], v[120:123]
	v_mfma_f32_16x16x32_bf16 v[116:119], v[154:157], v[196:199], v[116:119]
	v_mfma_f32_16x16x32_bf16 v[112:115], v[162:165], v[196:199], v[112:115]
	v_mfma_f32_16x16x32_bf16 v[100:103], v[154:157], v[204:207], v[100:103]
	v_mfma_f32_16x16x32_bf16 v[96:99], v[162:165], v[204:207], v[96:99]
	v_mfma_f32_16x16x32_bf16 v[84:87], v[154:157], v[212:215], v[84:87]
	v_mfma_f32_16x16x32_bf16 v[80:83], v[162:165], v[212:215], v[80:83]
	v_mfma_f32_16x16x32_bf16 v[108:111], v[166:169], v[184:187], v[108:111]
	v_mfma_f32_16x16x32_bf16 v[104:107], v[174:177], v[184:187], v[104:107]
	v_mfma_f32_16x16x32_bf16 v[92:95], v[166:169], v[192:195], v[92:95]
	v_mfma_f32_16x16x32_bf16 v[88:91], v[174:177], v[192:195], v[88:91]
	v_mfma_f32_16x16x32_bf16 v[76:79], v[166:169], v[200:203], v[76:79]
	v_mfma_f32_16x16x32_bf16 v[72:75], v[174:177], v[200:203], v[72:75]
	v_mfma_f32_16x16x32_bf16 v[68:71], v[166:169], v[208:211], v[68:71]
	v_mfma_f32_16x16x32_bf16 v[64:67], v[174:177], v[208:211], v[64:67]
	v_mfma_f32_16x16x32_bf16 v[108:111], v[170:173], v[188:191], v[108:111]
	v_mfma_f32_16x16x32_bf16 v[104:107], v[178:181], v[188:191], v[104:107]
	v_mfma_f32_16x16x32_bf16 v[92:95], v[170:173], v[196:199], v[92:95]
	v_mfma_f32_16x16x32_bf16 v[88:91], v[178:181], v[196:199], v[88:91]
	v_mfma_f32_16x16x32_bf16 v[76:79], v[170:173], v[204:207], v[76:79]
	v_mfma_f32_16x16x32_bf16 v[72:75], v[178:181], v[204:207], v[72:75]
	v_mfma_f32_16x16x32_bf16 v[68:71], v[170:173], v[212:215], v[68:71]
	v_mfma_f32_16x16x32_bf16 v[64:67], v[178:181], v[212:215], v[64:67]
	s_setprio 0
	s_barrier
	s_add_i32 s28, s58, s36
	v_lshl_add_u64 v[216:217], v[216:217], 0, s[10:11]
	s_mov_b32 m0, s28
	ds_read_b128 v[184:187], v149 offset:49152
	ds_read_b128 v[188:191], v149 offset:50176
	ds_read_b128 v[192:195], v149 offset:51200
	ds_read_b128 v[196:199], v149 offset:52224
	ds_read_b128 v[200:203], v149 offset:53248
	ds_read_b128 v[204:207], v149 offset:54272
	ds_read_b128 v[208:211], v149 offset:55296
	ds_read_b128 v[212:215], v149 offset:56320
	global_load_lds_dwordx4 v[216:217], off
	s_add_i32 m0, s28, 0x2000
	s_add_u32 s26, s26, 0xb0080
	v_lshl_add_u64 v[216:217], v[218:219], 0, s[10:11]
	s_addc_u32 s27, s27, 0
	s_add_i32 s28, s59, s36
	global_load_lds_dwordx4 v[216:217], off
	v_lshl_add_u64 v[216:217], s[26:27], 0, v[130:131]
	s_mov_b32 m0, s28
	s_nop 0
	global_load_lds_dwordx4 v[216:217], off
	v_lshl_add_u64 v[216:217], s[26:27], 0, v[134:135]
	s_add_i32 m0, s28, 0x2000
	s_nop 0
	global_load_lds_dwordx4 v[216:217], off
	v_lshl_add_u64 v[216:217], v[220:221], 0, s[10:11]
	s_mov_b32 m0, s43
	s_nop 0
	global_load_lds_dwordx4 v[216:217], off
	v_lshl_add_u64 v[216:217], v[222:223], 0, s[10:11]
	s_mov_b32 m0, s44
	s_nop 0
	global_load_lds_dwordx4 v[216:217], off
	s_waitcnt vmcnt(8)
	s_waitcnt lgkmcnt(0)
	s_barrier
	s_setprio 1
	v_mfma_f32_16x16x32_bf16 v[60:63], v[150:153], v[184:187], v[60:63]
	v_mfma_f32_16x16x32_bf16 v[56:59], v[158:161], v[184:187], v[56:59]
	v_mfma_f32_16x16x32_bf16 v[52:55], v[150:153], v[192:195], v[52:55]
	v_mfma_f32_16x16x32_bf16 v[48:51], v[158:161], v[192:195], v[48:51]
	v_mfma_f32_16x16x32_bf16 v[36:39], v[150:153], v[200:203], v[36:39]
	v_mfma_f32_16x16x32_bf16 v[32:35], v[158:161], v[200:203], v[32:35]
	v_mfma_f32_16x16x32_bf16 v[20:23], v[150:153], v[208:211], v[20:23]
	v_mfma_f32_16x16x32_bf16 v[16:19], v[158:161], v[208:211], v[16:19]
	v_mfma_f32_16x16x32_bf16 v[60:63], v[154:157], v[188:191], v[60:63]
	v_mfma_f32_16x16x32_bf16 v[56:59], v[162:165], v[188:191], v[56:59]
	v_mfma_f32_16x16x32_bf16 v[52:55], v[154:157], v[196:199], v[52:55]
	v_mfma_f32_16x16x32_bf16 v[48:51], v[162:165], v[196:199], v[48:51]
	v_mfma_f32_16x16x32_bf16 v[36:39], v[154:157], v[204:207], v[36:39]
	v_mfma_f32_16x16x32_bf16 v[32:35], v[162:165], v[204:207], v[32:35]
	v_mfma_f32_16x16x32_bf16 v[20:23], v[154:157], v[212:215], v[20:23]
	v_mfma_f32_16x16x32_bf16 v[16:19], v[162:165], v[212:215], v[16:19]
	v_mfma_f32_16x16x32_bf16 v[44:47], v[166:169], v[184:187], v[44:47]
	v_mfma_f32_16x16x32_bf16 v[40:43], v[174:177], v[184:187], v[40:43]
	v_mfma_f32_16x16x32_bf16 v[28:31], v[166:169], v[192:195], v[28:31]
	v_mfma_f32_16x16x32_bf16 v[24:27], v[174:177], v[192:195], v[24:27]
	v_mfma_f32_16x16x32_bf16 v[12:15], v[166:169], v[200:203], v[12:15]
	v_mfma_f32_16x16x32_bf16 v[8:11], v[174:177], v[200:203], v[8:11]
	v_mfma_f32_16x16x32_bf16 v[4:7], v[166:169], v[208:211], v[4:7]
	v_mfma_f32_16x16x32_bf16 v[0:3], v[174:177], v[208:211], v[0:3]
	v_mfma_f32_16x16x32_bf16 v[44:47], v[170:173], v[188:191], v[44:47]
	v_mfma_f32_16x16x32_bf16 v[40:43], v[178:181], v[188:191], v[40:43]
	v_mfma_f32_16x16x32_bf16 v[28:31], v[170:173], v[196:199], v[28:31]
	v_mfma_f32_16x16x32_bf16 v[24:27], v[178:181], v[196:199], v[24:27]
	v_mfma_f32_16x16x32_bf16 v[12:15], v[170:173], v[204:207], v[12:15]
	v_mfma_f32_16x16x32_bf16 v[8:11], v[178:181], v[204:207], v[8:11]
	v_mfma_f32_16x16x32_bf16 v[4:7], v[170:173], v[212:215], v[4:7]
	v_mfma_f32_16x16x32_bf16 v[0:3], v[178:181], v[212:215], v[0:3]
	s_setprio 0
	s_barrier
	s_add_i32 s57, s57, 2
	s_add_u32 s24, s24, 0x100
	s_addc_u32 s25, s25, 0
	s_add_u32 s55, s55, 0x100
	s_addc_u32 s56, s56, 0
	s_cmp_gt_u32 s57, 41
	s_cbranch_scc0 .LBB0_338
	s_and_b64 vcc, exec, s[12:13]
	s_cbranch_vccz .LBB0_341
	s_barrier

.LBB0_475:
	ds_read_b128 v[150:153], v158
	ds_read_b128 v[162:165], v158 offset:1024
	ds_read_b128 v[166:169], v158 offset:2048
	ds_read_b128 v[170:173], v158 offset:3072
	ds_read_b128 v[174:177], v159
	ds_read_b128 v[178:181], v159 offset:1024
	ds_read_b128 v[184:187], v159 offset:2048
	ds_read_b128 v[188:191], v159 offset:3072
	s_add_u32 s48, s46, 0xfffc0080
	s_addc_u32 s49, s47, -1
	s_cmp_eq_u32 s77, 12
	s_cselect_b32 s51, s1, s49
	s_cselect_b32 s50, s39, s48
	s_cselect_b32 s49, s37, s76
	s_cselect_b32 s48, s45, s75
	v_lshl_add_u64 v[224:225], s[46:47], 0, v[142:143]
	s_add_i32 m0, s57, 0xc000
	ds_read_b128 v[192:195], v160
	ds_read_b128 v[196:199], v160 offset:1024
	ds_read_b128 v[200:203], v160 offset:2048
	ds_read_b128 v[204:207], v160 offset:3072
	ds_read_b128 v[208:211], v160 offset:4096
	ds_read_b128 v[212:215], v160 offset:5120
	ds_read_b128 v[216:219], v160 offset:6144
	ds_read_b128 v[220:223], v160 offset:7168
	global_load_lds_dwordx4 v[224:225], off
	v_lshl_add_u64 v[224:225], s[46:47], 0, v[144:145]
	s_add_i32 m0, s57, 0xe000
	s_nop 0
	global_load_lds_dwordx4 v[224:225], off
	s_waitcnt vmcnt(8)
	s_waitcnt lgkmcnt(0)
	s_barrier
	s_setprio 1
	v_mfma_f32_16x16x32_bf16 v[64:67], v[150:153], v[192:195], v[64:67]
	v_mfma_f32_16x16x32_bf16 v[28:31], v[166:169], v[192:195], v[28:31]
	v_mfma_f32_16x16x32_bf16 v[60:63], v[150:153], v[200:203], v[60:63]
	v_mfma_f32_16x16x32_bf16 v[24:27], v[166:169], v[200:203], v[24:27]
	v_mfma_f32_16x16x32_bf16 v[56:59], v[150:153], v[208:211], v[56:59]
	v_mfma_f32_16x16x32_bf16 v[20:23], v[166:169], v[208:211], v[20:23]
	v_mfma_f32_16x16x32_bf16 v[52:55], v[150:153], v[216:219], v[52:55]
	v_mfma_f32_16x16x32_bf16 v[16:19], v[166:169], v[216:219], v[16:19]
	v_mfma_f32_16x16x32_bf16 v[64:67], v[162:165], v[196:199], v[64:67]
	v_mfma_f32_16x16x32_bf16 v[28:31], v[170:173], v[196:199], v[28:31]
	v_mfma_f32_16x16x32_bf16 v[60:63], v[162:165], v[204:207], v[60:63]
	v_mfma_f32_16x16x32_bf16 v[24:27], v[170:173], v[204:207], v[24:27]
	v_mfma_f32_16x16x32_bf16 v[56:59], v[162:165], v[212:215], v[56:59]
	v_mfma_f32_16x16x32_bf16 v[20:23], v[170:173], v[212:215], v[20:23]
	v_mfma_f32_16x16x32_bf16 v[52:55], v[162:165], v[220:223], v[52:55]
	v_mfma_f32_16x16x32_bf16 v[16:19], v[170:173], v[220:223], v[16:19]
	v_mfma_f32_16x16x32_bf16 v[124:127], v[174:177], v[192:195], v[124:127]
	v_mfma_f32_16x16x32_bf16 v[120:123], v[184:187], v[192:195], v[120:123]
	v_mfma_f32_16x16x32_bf16 v[116:119], v[174:177], v[200:203], v[116:119]
	v_mfma_f32_16x16x32_bf16 v[112:115], v[184:187], v[200:203], v[112:115]
	v_mfma_f32_16x16x32_bf16 v[108:111], v[174:177], v[208:211], v[108:111]
	v_mfma_f32_16x16x32_bf16 v[104:107], v[184:187], v[208:211], v[104:107]
	v_mfma_f32_16x16x32_bf16 v[100:103], v[174:177], v[216:219], v[100:103]
	v_mfma_f32_16x16x32_bf16 v[96:99], v[184:187], v[216:219], v[96:99]
	v_mfma_f32_16x16x32_bf16 v[124:127], v[178:181], v[196:199], v[124:127]
	v_mfma_f32_16x16x32_bf16 v[120:123], v[188:191], v[196:199], v[120:123]
	v_mfma_f32_16x16x32_bf16 v[116:119], v[178:181], v[204:207], v[116:119]
	v_mfma_f32_16x16x32_bf16 v[112:115], v[188:191], v[204:207], v[112:115]
	v_mfma_f32_16x16x32_bf16 v[108:111], v[178:181], v[212:215], v[108:111]
	v_mfma_f32_16x16x32_bf16 v[104:107], v[188:191], v[212:215], v[104:107]
	v_mfma_f32_16x16x32_bf16 v[100:103], v[178:181], v[220:223], v[100:103]
	v_mfma_f32_16x16x32_bf16 v[96:99], v[188:191], v[220:223], v[96:99]
	s_setprio 0
	s_barrier
	s_add_i32 s78, s66, s56
	v_lshl_add_u64 v[224:225], s[48:49], 0, v[130:131]
	s_mov_b32 m0, s78
	ds_read_b128 v[192:195], v160 offset:16384
	ds_read_b128 v[196:199], v160 offset:17408
	ds_read_b128 v[200:203], v160 offset:18432
	ds_read_b128 v[204:207], v160 offset:19456
	ds_read_b128 v[208:211], v160 offset:20480
	ds_read_b128 v[212:215], v160 offset:21504
	ds_read_b128 v[216:219], v160 offset:22528
	ds_read_b128 v[220:223], v160 offset:23552
	global_load_lds_dwordx4 v[224:225], off
	s_add_i32 m0, s78, 0x2000
	s_add_u32 s78, s48, 0x40000
	v_lshl_add_u64 v[226:227], s[48:49], 0, v[134:135]
	s_addc_u32 s79, s49, 0
	s_add_i32 s80, s67, s56
	global_load_lds_dwordx4 v[226:227], off
	v_lshl_add_u64 v[228:229], s[78:79], 0, v[130:131]
	s_mov_b32 m0, s80
	v_lshl_add_u64 v[230:231], s[50:51], 0, v[132:133]
	global_load_lds_dwordx4 v[228:229], off
	v_lshl_add_u64 v[228:229], s[78:79], 0, v[134:135]
	s_add_i32 m0, s80, 0x2000
	s_nop 0
	global_load_lds_dwordx4 v[228:229], off
	v_lshl_add_u64 v[228:229], s[50:51], 0, v[128:129]
	s_mov_b32 m0, s57
	s_nop 0
	global_load_lds_dwordx4 v[228:229], off
	s_mov_b32 m0, s58
	s_nop 0
	global_load_lds_dwordx4 v[230:231], off
	s_waitcnt vmcnt(8)
	s_waitcnt lgkmcnt(0)
	s_barrier
	s_setprio 1
	v_mfma_f32_16x16x32_bf16 v[44:47], v[150:153], v[192:195], v[44:47]
	v_mfma_f32_16x16x32_bf16 v[12:15], v[166:169], v[192:195], v[12:15]
	v_mfma_f32_16x16x32_bf16 v[40:43], v[150:153], v[200:203], v[40:43]
	v_mfma_f32_16x16x32_bf16 v[8:11], v[166:169], v[200:203], v[8:11]
	v_mfma_f32_16x16x32_bf16 v[36:39], v[150:153], v[208:211], v[36:39]
	v_mfma_f32_16x16x32_bf16 v[4:7], v[166:169], v[208:211], v[4:7]
	v_mfma_f32_16x16x32_bf16 v[32:35], v[150:153], v[216:219], v[32:35]
	v_mfma_f32_16x16x32_bf16 v[0:3], v[166:169], v[216:219], v[0:3]
	v_mfma_f32_16x16x32_bf16 v[44:47], v[162:165], v[196:199], v[44:47]
	v_mfma_f32_16x16x32_bf16 v[12:15], v[170:173], v[196:199], v[12:15]
	v_mfma_f32_16x16x32_bf16 v[40:43], v[162:165], v[204:207], v[40:43]
	v_mfma_f32_16x16x32_bf16 v[8:11], v[170:173], v[204:207], v[8:11]
	v_mfma_f32_16x16x32_bf16 v[36:39], v[162:165], v[212:215], v[36:39]
	v_mfma_f32_16x16x32_bf16 v[4:7], v[170:173], v[212:215], v[4:7]
	v_mfma_f32_16x16x32_bf16 v[32:35], v[162:165], v[220:223], v[32:35]
	v_mfma_f32_16x16x32_bf16 v[0:3], v[170:173], v[220:223], v[0:3]
	v_mfma_f32_16x16x32_bf16 v[92:95], v[174:177], v[192:195], v[92:95]
	v_mfma_f32_16x16x32_bf16 v[88:91], v[184:187], v[192:195], v[88:91]
	v_mfma_f32_16x16x32_bf16 v[84:87], v[174:177], v[200:203], v[84:87]
	v_mfma_f32_16x16x32_bf16 v[80:83], v[184:187], v[200:203], v[80:83]
	v_mfma_f32_16x16x32_bf16 v[76:79], v[174:177], v[208:211], v[76:79]
	v_mfma_f32_16x16x32_bf16 v[72:75], v[184:187], v[208:211], v[72:75]
	v_mfma_f32_16x16x32_bf16 v[68:71], v[174:177], v[216:219], v[68:71]
	v_mfma_f32_16x16x32_bf16 v[48:51], v[184:187], v[216:219], v[48:51]
	v_mfma_f32_16x16x32_bf16 v[92:95], v[178:181], v[196:199], v[92:95]
	v_mfma_f32_16x16x32_bf16 v[88:91], v[188:191], v[196:199], v[88:91]
	v_mfma_f32_16x16x32_bf16 v[84:87], v[178:181], v[204:207], v[84:87]
	v_mfma_f32_16x16x32_bf16 v[80:83], v[188:191], v[204:207], v[80:83]
	v_mfma_f32_16x16x32_bf16 v[76:79], v[178:181], v[212:215], v[76:79]
	v_mfma_f32_16x16x32_bf16 v[72:75], v[188:191], v[212:215], v[72:75]
	v_mfma_f32_16x16x32_bf16 v[68:71], v[178:181], v[220:223], v[68:71]
	v_mfma_f32_16x16x32_bf16 v[48:51], v[188:191], v[220:223], v[48:51]
	s_setprio 0
	s_barrier
	s_add_i32 s78, 0, 0x18000
	v_add_u32_e32 v136, s78, v156
	s_add_i32 s79, 0, 0x1c000
	ds_read_b128 v[150:153], v136
	ds_read_b128 v[162:165], v136 offset:1024
	ds_read_b128 v[166:169], v136 offset:2048
	ds_read_b128 v[170:173], v136 offset:3072
	v_add_u32_e32 v136, s79, v156
	ds_read_b128 v[174:177], v136
	ds_read_b128 v[178:181], v136 offset:1024
	ds_read_b128 v[184:187], v136 offset:2048
	ds_read_b128 v[188:191], v136 offset:3072
	s_add_u32 s50, s50, 0x40000
	s_addc_u32 s51, s51, 0
	s_mov_b32 m0, s59
	v_lshl_add_u64 v[232:233], s[50:51], 0, v[128:129]
	ds_read_b128 v[192:195], v160 offset:32768
	ds_read_b128 v[196:199], v160 offset:33792
	ds_read_b128 v[200:203], v160 offset:34816
	ds_read_b128 v[204:207], v160 offset:35840
	ds_read_b128 v[208:211], v160 offset:36864
	ds_read_b128 v[212:215], v160 offset:37888
	ds_read_b128 v[216:219], v160 offset:38912
	ds_read_b128 v[220:223], v160 offset:39936
	global_load_lds_dwordx4 v[232:233], off
	v_lshl_add_u64 v[232:233], s[50:51], 0, v[132:133]
	s_mov_b32 m0, s60
	s_nop 0
	global_load_lds_dwordx4 v[232:233], off
	s_waitcnt vmcnt(8)
	s_waitcnt lgkmcnt(0)
	s_barrier
	s_setprio 1
	v_mfma_f32_16x16x32_bf16 v[64:67], v[150:153], v[192:195], v[64:67]
	v_mfma_f32_16x16x32_bf16 v[28:31], v[166:169], v[192:195], v[28:31]
	v_mfma_f32_16x16x32_bf16 v[60:63], v[150:153], v[200:203], v[60:63]
	v_mfma_f32_16x16x32_bf16 v[24:27], v[166:169], v[200:203], v[24:27]
	v_mfma_f32_16x16x32_bf16 v[56:59], v[150:153], v[208:211], v[56:59]
	v_mfma_f32_16x16x32_bf16 v[20:23], v[166:169], v[208:211], v[20:23]
	v_mfma_f32_16x16x32_bf16 v[52:55], v[150:153], v[216:219], v[52:55]
	v_mfma_f32_16x16x32_bf16 v[16:19], v[166:169], v[216:219], v[16:19]
	v_mfma_f32_16x16x32_bf16 v[64:67], v[162:165], v[196:199], v[64:67]
	v_mfma_f32_16x16x32_bf16 v[28:31], v[170:173], v[196:199], v[28:31]
	v_mfma_f32_16x16x32_bf16 v[60:63], v[162:165], v[204:207], v[60:63]
	v_mfma_f32_16x16x32_bf16 v[24:27], v[170:173], v[204:207], v[24:27]
	v_mfma_f32_16x16x32_bf16 v[56:59], v[162:165], v[212:215], v[56:59]
	v_mfma_f32_16x16x32_bf16 v[20:23], v[170:173], v[212:215], v[20:23]
	v_mfma_f32_16x16x32_bf16 v[52:55], v[162:165], v[220:223], v[52:55]
	v_mfma_f32_16x16x32_bf16 v[16:19], v[170:173], v[220:223], v[16:19]
	v_mfma_f32_16x16x32_bf16 v[124:127], v[174:177], v[192:195], v[124:127]
	v_mfma_f32_16x16x32_bf16 v[120:123], v[184:187], v[192:195], v[120:123]
	v_mfma_f32_16x16x32_bf16 v[116:119], v[174:177], v[200:203], v[116:119]
	v_mfma_f32_16x16x32_bf16 v[112:115], v[184:187], v[200:203], v[112:115]
	v_mfma_f32_16x16x32_bf16 v[108:111], v[174:177], v[208:211], v[108:111]
	v_mfma_f32_16x16x32_bf16 v[104:107], v[184:187], v[208:211], v[104:107]
	v_mfma_f32_16x16x32_bf16 v[100:103], v[174:177], v[216:219], v[100:103]
	v_mfma_f32_16x16x32_bf16 v[96:99], v[184:187], v[216:219], v[96:99]
	v_mfma_f32_16x16x32_bf16 v[124:127], v[178:181], v[196:199], v[124:127]
	v_mfma_f32_16x16x32_bf16 v[120:123], v[188:191], v[196:199], v[120:123]
	v_mfma_f32_16x16x32_bf16 v[116:119], v[178:181], v[204:207], v[116:119]
	v_mfma_f32_16x16x32_bf16 v[112:115], v[188:191], v[204:207], v[112:115]
	v_mfma_f32_16x16x32_bf16 v[108:111], v[178:181], v[212:215], v[108:111]
	v_mfma_f32_16x16x32_bf16 v[104:107], v[188:191], v[212:215], v[104:107]
	v_mfma_f32_16x16x32_bf16 v[100:103], v[178:181], v[220:223], v[100:103]
	v_mfma_f32_16x16x32_bf16 v[96:99], v[188:191], v[220:223], v[96:99]
	s_setprio 0
	s_barrier
	s_add_i32 s50, s78, s56
	v_lshl_add_u64 v[224:225], v[224:225], 0, s[28:29]
	s_mov_b32 m0, s50
	ds_read_b128 v[192:195], v160 offset:49152
	ds_read_b128 v[196:199], v160 offset:50176
	ds_read_b128 v[200:203], v160 offset:51200
	ds_read_b128 v[204:207], v160 offset:52224
	ds_read_b128 v[208:211], v160 offset:53248
	ds_read_b128 v[212:215], v160 offset:54272
	ds_read_b128 v[216:219], v160 offset:55296
	ds_read_b128 v[220:223], v160 offset:56320
	global_load_lds_dwordx4 v[224:225], off
	s_add_i32 m0, s50, 0x2000
	s_add_u32 s48, s48, 0x40080
	v_lshl_add_u64 v[224:225], v[226:227], 0, s[28:29]
	s_addc_u32 s49, s49, 0
	s_add_i32 s50, s79, s56
	global_load_lds_dwordx4 v[224:225], off
	v_lshl_add_u64 v[224:225], s[48:49], 0, v[130:131]
	s_mov_b32 m0, s50
	s_nop 0
	global_load_lds_dwordx4 v[224:225], off
	v_lshl_add_u64 v[224:225], s[48:49], 0, v[134:135]
	s_add_i32 m0, s50, 0x2000
	s_nop 0
	global_load_lds_dwordx4 v[224:225], off
	v_lshl_add_u64 v[224:225], v[228:229], 0, s[28:29]
	s_mov_b32 m0, s63
	s_nop 0
	global_load_lds_dwordx4 v[224:225], off
	v_lshl_add_u64 v[224:225], v[230:231], 0, s[28:29]
	s_mov_b32 m0, s64
	s_nop 0
	global_load_lds_dwordx4 v[224:225], off
	s_waitcnt vmcnt(8)
	s_waitcnt lgkmcnt(0)
	s_barrier
	s_setprio 1
	v_mfma_f32_16x16x32_bf16 v[44:47], v[150:153], v[192:195], v[44:47]
	v_mfma_f32_16x16x32_bf16 v[12:15], v[166:169], v[192:195], v[12:15]
	v_mfma_f32_16x16x32_bf16 v[40:43], v[150:153], v[200:203], v[40:43]
	v_mfma_f32_16x16x32_bf16 v[8:11], v[166:169], v[200:203], v[8:11]
	v_mfma_f32_16x16x32_bf16 v[36:39], v[150:153], v[208:211], v[36:39]
	v_mfma_f32_16x16x32_bf16 v[4:7], v[166:169], v[208:211], v[4:7]
	v_mfma_f32_16x16x32_bf16 v[32:35], v[150:153], v[216:219], v[32:35]
	v_mfma_f32_16x16x32_bf16 v[0:3], v[166:169], v[216:219], v[0:3]
	v_mfma_f32_16x16x32_bf16 v[44:47], v[162:165], v[196:199], v[44:47]
	v_mfma_f32_16x16x32_bf16 v[12:15], v[170:173], v[196:199], v[12:15]
	v_mfma_f32_16x16x32_bf16 v[40:43], v[162:165], v[204:207], v[40:43]
	v_mfma_f32_16x16x32_bf16 v[8:11], v[170:173], v[204:207], v[8:11]
	v_mfma_f32_16x16x32_bf16 v[36:39], v[162:165], v[212:215], v[36:39]
	v_mfma_f32_16x16x32_bf16 v[4:7], v[170:173], v[212:215], v[4:7]
	v_mfma_f32_16x16x32_bf16 v[32:35], v[162:165], v[220:223], v[32:35]
	v_mfma_f32_16x16x32_bf16 v[0:3], v[170:173], v[220:223], v[0:3]
	v_mfma_f32_16x16x32_bf16 v[92:95], v[174:177], v[192:195], v[92:95]
	v_mfma_f32_16x16x32_bf16 v[88:91], v[184:187], v[192:195], v[88:91]
	v_mfma_f32_16x16x32_bf16 v[84:87], v[174:177], v[200:203], v[84:87]
	v_mfma_f32_16x16x32_bf16 v[80:83], v[184:187], v[200:203], v[80:83]
	v_mfma_f32_16x16x32_bf16 v[76:79], v[174:177], v[208:211], v[76:79]
	v_mfma_f32_16x16x32_bf16 v[72:75], v[184:187], v[208:211], v[72:75]
	v_mfma_f32_16x16x32_bf16 v[68:71], v[174:177], v[216:219], v[68:71]
	v_mfma_f32_16x16x32_bf16 v[48:51], v[184:187], v[216:219], v[48:51]
	v_mfma_f32_16x16x32_bf16 v[92:95], v[178:181], v[196:199], v[92:95]
	v_mfma_f32_16x16x32_bf16 v[88:91], v[188:191], v[196:199], v[88:91]
	v_mfma_f32_16x16x32_bf16 v[84:87], v[178:181], v[204:207], v[84:87]
	v_mfma_f32_16x16x32_bf16 v[80:83], v[188:191], v[204:207], v[80:83]
	v_mfma_f32_16x16x32_bf16 v[76:79], v[178:181], v[212:215], v[76:79]
	v_mfma_f32_16x16x32_bf16 v[72:75], v[188:191], v[212:215], v[72:75]
	v_mfma_f32_16x16x32_bf16 v[68:71], v[178:181], v[220:223], v[68:71]
	v_mfma_f32_16x16x32_bf16 v[48:51], v[188:191], v[220:223], v[48:51]
	s_setprio 0
	s_barrier
	s_add_i32 s77, s77, 2
	s_add_u32 s46, s46, 0x100
	s_addc_u32 s47, s47, 0
	s_add_u32 s75, s75, 0x100
	s_addc_u32 s76, s76, 0
	s_cmp_gt_u32 s77, 13
	s_cbranch_scc0 .LBB0_475
	s_and_b64 vcc, exec, s[30:31]
	s_cbranch_vccnz .LBB0_479
	v_lshl_add_u32 v162, s44, 8, v155
	s_cmp_lg_u32 s0, 22
	s_mov_b64 s[44:45], -1
	s_cbranch_scc1 .LBB0_480

.LBB0_1274:
	ds_read_b128 v[150:153], v147
	ds_read_b128 v[154:157], v147 offset:1024
	ds_read_b128 v[158:161], v147 offset:2048
	ds_read_b128 v[162:165], v147 offset:3072
	ds_read_b128 v[166:169], v148
	ds_read_b128 v[170:173], v148 offset:1024
	ds_read_b128 v[174:177], v148 offset:2048
	ds_read_b128 v[178:181], v148 offset:3072
	s_add_u32 s28, s4, 0xffea0080
	s_addc_u32 s29, s5, -1
	s_cmp_eq_u32 s59, 28
	s_cselect_b32 s31, s25, s29
	s_cselect_b32 s30, s24, s28
	s_cselect_b32 s29, s23, s58
	s_cselect_b32 s28, s56, s57
	v_lshl_add_u64 v[216:217], s[4:5], 0, v[136:137]
	s_add_i32 m0, s39, 0xc000
	ds_read_b128 v[184:187], v149
	ds_read_b128 v[188:191], v149 offset:1024
	ds_read_b128 v[192:195], v149 offset:2048
	ds_read_b128 v[196:199], v149 offset:3072
	ds_read_b128 v[200:203], v149 offset:4096
	ds_read_b128 v[204:207], v149 offset:5120
	ds_read_b128 v[208:211], v149 offset:6144
	ds_read_b128 v[212:215], v149 offset:7168
	global_load_lds_dwordx4 v[216:217], off
	v_lshl_add_u64 v[216:217], s[4:5], 0, v[138:139]
	s_add_i32 m0, s39, 0xe000
	s_nop 0
	global_load_lds_dwordx4 v[216:217], off
	s_waitcnt vmcnt(8)
	s_waitcnt lgkmcnt(0)
	s_barrier
	s_setprio 1
	v_mfma_f32_16x16x32_bf16 v[124:127], v[150:153], v[184:187], v[124:127]
	v_mfma_f32_16x16x32_bf16 v[120:123], v[158:161], v[184:187], v[120:123]
	v_mfma_f32_16x16x32_bf16 v[116:119], v[150:153], v[192:195], v[116:119]
	v_mfma_f32_16x16x32_bf16 v[112:115], v[158:161], v[192:195], v[112:115]
	v_mfma_f32_16x16x32_bf16 v[100:103], v[150:153], v[200:203], v[100:103]
	v_mfma_f32_16x16x32_bf16 v[96:99], v[158:161], v[200:203], v[96:99]
	v_mfma_f32_16x16x32_bf16 v[84:87], v[150:153], v[208:211], v[84:87]
	v_mfma_f32_16x16x32_bf16 v[80:83], v[158:161], v[208:211], v[80:83]
	v_mfma_f32_16x16x32_bf16 v[124:127], v[154:157], v[188:191], v[124:127]
	v_mfma_f32_16x16x32_bf16 v[120:123], v[162:165], v[188:191], v[120:123]
	v_mfma_f32_16x16x32_bf16 v[116:119], v[154:157], v[196:199], v[116:119]
	v_mfma_f32_16x16x32_bf16 v[112:115], v[162:165], v[196:199], v[112:115]
	v_mfma_f32_16x16x32_bf16 v[100:103], v[154:157], v[204:207], v[100:103]
	v_mfma_f32_16x16x32_bf16 v[96:99], v[162:165], v[204:207], v[96:99]
	v_mfma_f32_16x16x32_bf16 v[84:87], v[154:157], v[212:215], v[84:87]
	v_mfma_f32_16x16x32_bf16 v[80:83], v[162:165], v[212:215], v[80:83]
	v_mfma_f32_16x16x32_bf16 v[108:111], v[166:169], v[184:187], v[108:111]
	v_mfma_f32_16x16x32_bf16 v[104:107], v[174:177], v[184:187], v[104:107]
	v_mfma_f32_16x16x32_bf16 v[92:95], v[166:169], v[192:195], v[92:95]
	v_mfma_f32_16x16x32_bf16 v[88:91], v[174:177], v[192:195], v[88:91]
	v_mfma_f32_16x16x32_bf16 v[76:79], v[166:169], v[200:203], v[76:79]
	v_mfma_f32_16x16x32_bf16 v[72:75], v[174:177], v[200:203], v[72:75]
	v_mfma_f32_16x16x32_bf16 v[68:71], v[166:169], v[208:211], v[68:71]
	v_mfma_f32_16x16x32_bf16 v[64:67], v[174:177], v[208:211], v[64:67]
	v_mfma_f32_16x16x32_bf16 v[108:111], v[170:173], v[188:191], v[108:111]
	v_mfma_f32_16x16x32_bf16 v[104:107], v[178:181], v[188:191], v[104:107]
	v_mfma_f32_16x16x32_bf16 v[92:95], v[170:173], v[196:199], v[92:95]
	v_mfma_f32_16x16x32_bf16 v[88:91], v[178:181], v[196:199], v[88:91]
	v_mfma_f32_16x16x32_bf16 v[76:79], v[170:173], v[204:207], v[76:79]
	v_mfma_f32_16x16x32_bf16 v[72:75], v[178:181], v[204:207], v[72:75]
	v_mfma_f32_16x16x32_bf16 v[68:71], v[170:173], v[212:215], v[68:71]
	v_mfma_f32_16x16x32_bf16 v[64:67], v[178:181], v[212:215], v[64:67]
	s_setprio 0
	s_barrier
	s_add_i32 s60, s47, s38
	v_lshl_add_u64 v[216:217], s[28:29], 0, v[130:131]
	s_mov_b32 m0, s60
	ds_read_b128 v[184:187], v149 offset:16384
	ds_read_b128 v[188:191], v149 offset:17408
	ds_read_b128 v[192:195], v149 offset:18432
	ds_read_b128 v[196:199], v149 offset:19456
	ds_read_b128 v[200:203], v149 offset:20480
	ds_read_b128 v[204:207], v149 offset:21504
	ds_read_b128 v[208:211], v149 offset:22528
	ds_read_b128 v[212:215], v149 offset:23552
	global_load_lds_dwordx4 v[216:217], off
	s_add_i32 m0, s60, 0x2000
	s_add_u32 s60, s28, 0x80000
	v_lshl_add_u64 v[218:219], s[28:29], 0, v[134:135]
	s_addc_u32 s61, s29, 0
	s_add_i32 s62, s48, s38
	global_load_lds_dwordx4 v[218:219], off
	v_lshl_add_u64 v[220:221], s[60:61], 0, v[130:131]
	s_mov_b32 m0, s62
	v_lshl_add_u64 v[222:223], s[30:31], 0, v[132:133]
	global_load_lds_dwordx4 v[220:221], off
	v_lshl_add_u64 v[220:221], s[60:61], 0, v[134:135]
	s_add_i32 m0, s62, 0x2000
	s_nop 0
	global_load_lds_dwordx4 v[220:221], off
	v_lshl_add_u64 v[220:221], s[30:31], 0, v[128:129]
	s_mov_b32 m0, s39
	s_nop 0
	global_load_lds_dwordx4 v[220:221], off
	s_mov_b32 m0, s40
	s_nop 0
	global_load_lds_dwordx4 v[222:223], off
	s_waitcnt vmcnt(8)
	s_waitcnt lgkmcnt(0)
	s_barrier
	s_setprio 1
	v_mfma_f32_16x16x32_bf16 v[60:63], v[150:153], v[184:187], v[60:63]
	v_mfma_f32_16x16x32_bf16 v[56:59], v[158:161], v[184:187], v[56:59]
	v_mfma_f32_16x16x32_bf16 v[52:55], v[150:153], v[192:195], v[52:55]
	v_mfma_f32_16x16x32_bf16 v[48:51], v[158:161], v[192:195], v[48:51]
	v_mfma_f32_16x16x32_bf16 v[36:39], v[150:153], v[200:203], v[36:39]
	v_mfma_f32_16x16x32_bf16 v[32:35], v[158:161], v[200:203], v[32:35]
	v_mfma_f32_16x16x32_bf16 v[20:23], v[150:153], v[208:211], v[20:23]
	v_mfma_f32_16x16x32_bf16 v[16:19], v[158:161], v[208:211], v[16:19]
	v_mfma_f32_16x16x32_bf16 v[60:63], v[154:157], v[188:191], v[60:63]
	v_mfma_f32_16x16x32_bf16 v[56:59], v[162:165], v[188:191], v[56:59]
	v_mfma_f32_16x16x32_bf16 v[52:55], v[154:157], v[196:199], v[52:55]
	v_mfma_f32_16x16x32_bf16 v[48:51], v[162:165], v[196:199], v[48:51]
	v_mfma_f32_16x16x32_bf16 v[36:39], v[154:157], v[204:207], v[36:39]
	v_mfma_f32_16x16x32_bf16 v[32:35], v[162:165], v[204:207], v[32:35]
	v_mfma_f32_16x16x32_bf16 v[20:23], v[154:157], v[212:215], v[20:23]
	v_mfma_f32_16x16x32_bf16 v[16:19], v[162:165], v[212:215], v[16:19]
	v_mfma_f32_16x16x32_bf16 v[44:47], v[166:169], v[184:187], v[44:47]
	v_mfma_f32_16x16x32_bf16 v[40:43], v[174:177], v[184:187], v[40:43]
	v_mfma_f32_16x16x32_bf16 v[28:31], v[166:169], v[192:195], v[28:31]
	v_mfma_f32_16x16x32_bf16 v[24:27], v[174:177], v[192:195], v[24:27]
	v_mfma_f32_16x16x32_bf16 v[12:15], v[166:169], v[200:203], v[12:15]
	v_mfma_f32_16x16x32_bf16 v[8:11], v[174:177], v[200:203], v[8:11]
	v_mfma_f32_16x16x32_bf16 v[4:7], v[166:169], v[208:211], v[4:7]
	v_mfma_f32_16x16x32_bf16 v[0:3], v[174:177], v[208:211], v[0:3]
	v_mfma_f32_16x16x32_bf16 v[44:47], v[170:173], v[188:191], v[44:47]
	v_mfma_f32_16x16x32_bf16 v[40:43], v[178:181], v[188:191], v[40:43]
	v_mfma_f32_16x16x32_bf16 v[28:31], v[170:173], v[196:199], v[28:31]
	v_mfma_f32_16x16x32_bf16 v[24:27], v[178:181], v[196:199], v[24:27]
	v_mfma_f32_16x16x32_bf16 v[12:15], v[170:173], v[204:207], v[12:15]
	v_mfma_f32_16x16x32_bf16 v[8:11], v[178:181], v[204:207], v[8:11]
	v_mfma_f32_16x16x32_bf16 v[4:7], v[170:173], v[212:215], v[4:7]
	v_mfma_f32_16x16x32_bf16 v[0:3], v[178:181], v[212:215], v[0:3]
	s_setprio 0
	s_barrier
	s_add_i32 s60, 0, 0x18000
	s_add_i32 s61, 0, 0x1c000
	v_add_u32_e32 v162, s60, v145
	v_add_u32_e32 v178, s61, v145
	ds_read_b128 v[150:153], v162
	ds_read_b128 v[154:157], v162 offset:1024
	ds_read_b128 v[158:161], v162 offset:2048
	ds_read_b128 v[162:165], v162 offset:3072
	ds_read_b128 v[166:169], v178
	ds_read_b128 v[170:173], v178 offset:1024
	ds_read_b128 v[174:177], v178 offset:2048
	ds_read_b128 v[178:181], v178 offset:3072
	s_add_u32 s30, s30, 0x160000
	s_addc_u32 s31, s31, 0
	s_mov_b32 m0, s41
	v_lshl_add_u64 v[224:225], s[30:31], 0, v[128:129]
	ds_read_b128 v[184:187], v149 offset:32768
	ds_read_b128 v[188:191], v149 offset:33792
	ds_read_b128 v[192:195], v149 offset:34816
	ds_read_b128 v[196:199], v149 offset:35840
	ds_read_b128 v[200:203], v149 offset:36864
	ds_read_b128 v[204:207], v149 offset:37888
	ds_read_b128 v[208:211], v149 offset:38912
	ds_read_b128 v[212:215], v149 offset:39936
	global_load_lds_dwordx4 v[224:225], off
	v_lshl_add_u64 v[224:225], s[30:31], 0, v[132:133]
	s_mov_b32 m0, s42
	s_nop 0
	global_load_lds_dwordx4 v[224:225], off
	s_waitcnt vmcnt(8)
	s_waitcnt lgkmcnt(0)
	s_barrier
	s_setprio 1
	v_mfma_f32_16x16x32_bf16 v[124:127], v[150:153], v[184:187], v[124:127]
	v_mfma_f32_16x16x32_bf16 v[120:123], v[158:161], v[184:187], v[120:123]
	v_mfma_f32_16x16x32_bf16 v[116:119], v[150:153], v[192:195], v[116:119]
	v_mfma_f32_16x16x32_bf16 v[112:115], v[158:161], v[192:195], v[112:115]
	v_mfma_f32_16x16x32_bf16 v[100:103], v[150:153], v[200:203], v[100:103]
	v_mfma_f32_16x16x32_bf16 v[96:99], v[158:161], v[200:203], v[96:99]
	v_mfma_f32_16x16x32_bf16 v[84:87], v[150:153], v[208:211], v[84:87]
	v_mfma_f32_16x16x32_bf16 v[80:83], v[158:161], v[208:211], v[80:83]
	v_mfma_f32_16x16x32_bf16 v[124:127], v[154:157], v[188:191], v[124:127]
	v_mfma_f32_16x16x32_bf16 v[120:123], v[162:165], v[188:191], v[120:123]
	v_mfma_f32_16x16x32_bf16 v[116:119], v[154:157], v[196:199], v[116:119]
	v_mfma_f32_16x16x32_bf16 v[112:115], v[162:165], v[196:199], v[112:115]
	v_mfma_f32_16x16x32_bf16 v[100:103], v[154:157], v[204:207], v[100:103]
	v_mfma_f32_16x16x32_bf16 v[96:99], v[162:165], v[204:207], v[96:99]
	v_mfma_f32_16x16x32_bf16 v[84:87], v[154:157], v[212:215], v[84:87]
	v_mfma_f32_16x16x32_bf16 v[80:83], v[162:165], v[212:215], v[80:83]
	v_mfma_f32_16x16x32_bf16 v[108:111], v[166:169], v[184:187], v[108:111]
	v_mfma_f32_16x16x32_bf16 v[104:107], v[174:177], v[184:187], v[104:107]
	v_mfma_f32_16x16x32_bf16 v[92:95], v[166:169], v[192:195], v[92:95]
	v_mfma_f32_16x16x32_bf16 v[88:91], v[174:177], v[192:195], v[88:91]
	v_mfma_f32_16x16x32_bf16 v[76:79], v[166:169], v[200:203], v[76:79]
	v_mfma_f32_16x16x32_bf16 v[72:75], v[174:177], v[200:203], v[72:75]
	v_mfma_f32_16x16x32_bf16 v[68:71], v[166:169], v[208:211], v[68:71]
	v_mfma_f32_16x16x32_bf16 v[64:67], v[174:177], v[208:211], v[64:67]
	v_mfma_f32_16x16x32_bf16 v[108:111], v[170:173], v[188:191], v[108:111]
	v_mfma_f32_16x16x32_bf16 v[104:107], v[178:181], v[188:191], v[104:107]
	v_mfma_f32_16x16x32_bf16 v[92:95], v[170:173], v[196:199], v[92:95]
	v_mfma_f32_16x16x32_bf16 v[88:91], v[178:181], v[196:199], v[88:91]
	v_mfma_f32_16x16x32_bf16 v[76:79], v[170:173], v[204:207], v[76:79]
	v_mfma_f32_16x16x32_bf16 v[72:75], v[178:181], v[204:207], v[72:75]
	v_mfma_f32_16x16x32_bf16 v[68:71], v[170:173], v[212:215], v[68:71]
	v_mfma_f32_16x16x32_bf16 v[64:67], v[178:181], v[212:215], v[64:67]
	s_setprio 0
	s_barrier
	s_add_i32 s30, s60, s38
	v_lshl_add_u64 v[216:217], v[216:217], 0, s[10:11]
	s_mov_b32 m0, s30
	ds_read_b128 v[184:187], v149 offset:49152
	ds_read_b128 v[188:191], v149 offset:50176
	ds_read_b128 v[192:195], v149 offset:51200
	ds_read_b128 v[196:199], v149 offset:52224
	ds_read_b128 v[200:203], v149 offset:53248
	ds_read_b128 v[204:207], v149 offset:54272
	ds_read_b128 v[208:211], v149 offset:55296
	ds_read_b128 v[212:215], v149 offset:56320
	global_load_lds_dwordx4 v[216:217], off
	s_add_i32 m0, s30, 0x2000
	s_add_u32 s28, s28, 0x80080
	v_lshl_add_u64 v[216:217], v[218:219], 0, s[10:11]
	s_addc_u32 s29, s29, 0
	s_add_i32 s30, s61, s38
	global_load_lds_dwordx4 v[216:217], off
	v_lshl_add_u64 v[216:217], s[28:29], 0, v[130:131]
	s_mov_b32 m0, s30
	s_nop 0
	global_load_lds_dwordx4 v[216:217], off
	v_lshl_add_u64 v[216:217], s[28:29], 0, v[134:135]
	s_add_i32 m0, s30, 0x2000
	s_nop 0
	global_load_lds_dwordx4 v[216:217], off
	v_lshl_add_u64 v[216:217], v[220:221], 0, s[10:11]
	s_mov_b32 m0, s45
	s_nop 0
	global_load_lds_dwordx4 v[216:217], off
	v_lshl_add_u64 v[216:217], v[222:223], 0, s[10:11]
	s_mov_b32 m0, s46
	s_nop 0
	global_load_lds_dwordx4 v[216:217], off
	s_waitcnt vmcnt(8)
	s_waitcnt lgkmcnt(0)
	s_barrier
	s_setprio 1
	v_mfma_f32_16x16x32_bf16 v[60:63], v[150:153], v[184:187], v[60:63]
	v_mfma_f32_16x16x32_bf16 v[56:59], v[158:161], v[184:187], v[56:59]
	v_mfma_f32_16x16x32_bf16 v[52:55], v[150:153], v[192:195], v[52:55]
	v_mfma_f32_16x16x32_bf16 v[48:51], v[158:161], v[192:195], v[48:51]
	v_mfma_f32_16x16x32_bf16 v[36:39], v[150:153], v[200:203], v[36:39]
	v_mfma_f32_16x16x32_bf16 v[32:35], v[158:161], v[200:203], v[32:35]
	v_mfma_f32_16x16x32_bf16 v[20:23], v[150:153], v[208:211], v[20:23]
	v_mfma_f32_16x16x32_bf16 v[16:19], v[158:161], v[208:211], v[16:19]
	v_mfma_f32_16x16x32_bf16 v[60:63], v[154:157], v[188:191], v[60:63]
	v_mfma_f32_16x16x32_bf16 v[56:59], v[162:165], v[188:191], v[56:59]
	v_mfma_f32_16x16x32_bf16 v[52:55], v[154:157], v[196:199], v[52:55]
	v_mfma_f32_16x16x32_bf16 v[48:51], v[162:165], v[196:199], v[48:51]
	v_mfma_f32_16x16x32_bf16 v[36:39], v[154:157], v[204:207], v[36:39]
	v_mfma_f32_16x16x32_bf16 v[32:35], v[162:165], v[204:207], v[32:35]
	v_mfma_f32_16x16x32_bf16 v[20:23], v[154:157], v[212:215], v[20:23]
	v_mfma_f32_16x16x32_bf16 v[16:19], v[162:165], v[212:215], v[16:19]
	v_mfma_f32_16x16x32_bf16 v[44:47], v[166:169], v[184:187], v[44:47]
	v_mfma_f32_16x16x32_bf16 v[40:43], v[174:177], v[184:187], v[40:43]
	v_mfma_f32_16x16x32_bf16 v[28:31], v[166:169], v[192:195], v[28:31]
	v_mfma_f32_16x16x32_bf16 v[24:27], v[174:177], v[192:195], v[24:27]
	v_mfma_f32_16x16x32_bf16 v[12:15], v[166:169], v[200:203], v[12:15]
	v_mfma_f32_16x16x32_bf16 v[8:11], v[174:177], v[200:203], v[8:11]
	v_mfma_f32_16x16x32_bf16 v[4:7], v[166:169], v[208:211], v[4:7]
	v_mfma_f32_16x16x32_bf16 v[0:3], v[174:177], v[208:211], v[0:3]
	v_mfma_f32_16x16x32_bf16 v[44:47], v[170:173], v[188:191], v[44:47]
	v_mfma_f32_16x16x32_bf16 v[40:43], v[178:181], v[188:191], v[40:43]
	v_mfma_f32_16x16x32_bf16 v[28:31], v[170:173], v[196:199], v[28:31]
	v_mfma_f32_16x16x32_bf16 v[24:27], v[178:181], v[196:199], v[24:27]
	v_mfma_f32_16x16x32_bf16 v[12:15], v[170:173], v[204:207], v[12:15]
	v_mfma_f32_16x16x32_bf16 v[8:11], v[178:181], v[204:207], v[8:11]
	v_mfma_f32_16x16x32_bf16 v[4:7], v[170:173], v[212:215], v[4:7]
	v_mfma_f32_16x16x32_bf16 v[0:3], v[178:181], v[212:215], v[0:3]
	s_setprio 0
	s_barrier
	s_add_i32 s59, s59, 2
	s_add_u32 s4, s4, 0x100
	s_addc_u32 s5, s5, 0
	s_add_u32 s57, s57, 0x100
	s_addc_u32 s58, s58, 0
	s_cmp_gt_u32 s59, 29
	s_cbranch_scc0 .LBB0_1274
	s_and_b64 vcc, exec, s[12:13]
	s_cbranch_vccz .LBB0_1277
	s_barrier
